# v17 + decode V loads without the nt hint too
# speedup vs baseline: 1.0146x; 1.0038x over previous
.LBB0_1241:
	s_or_b64 exec, exec, s[10:11]
	s_lshl_b32 s0, s13, 2
	s_and_b32 s0, s0, -16
	s_ashr_i32 s1, s0, 31
	s_lshl_b32 s14, s43, 7
	s_and_b32 s15, s42, 7
	s_lshl_b64 s[0:1], s[0:1], 2
	s_add_u32 s0, s60, s0
	s_addc_u32 s1, s61, s1
	s_lshl_b32 s10, s15, 3
	v_mov_b32_e32 v2, s10
	global_load_dword v4, v2, s[0:1]
	v_lshlrev_b32_e32 v5, 13, v139
	v_lshl_or_b32 v6, v123, 4, v5
	s_lshl_b32 s13, s14, 2
	v_lshlrev_b32_e32 v2, 5, v139
	v_mov_b32_e32 v7, v3
	v_lshl_add_u32 v2, v123, 11, v2
	s_lshl_b32 s10, s43, 9
	v_lshlrev_b32_e32 v124, 2, v139
	v_lshl_add_u64 v[128:129], s[56:57], 0, v[2:3]
	s_lshl_b32 s22, s15, 8
	s_add_i32 s43, s10, 0
	v_lshl_add_u64 v[130:131], s[58:59], 0, v[6:7]
	v_sub_u32_e32 v141, v125, v124
	s_add_i32 s43, s43, 0x26a00
	s_waitcnt vmcnt(4)
	v_subrev_u32_e32 v142, s22, v141
	s_mov_b32 s68, 0
	v_mov_b32_e32 v138, 0
	v_mov_b32_e32 v140, 0xf149f2ca
	s_mov_b32 s69, 16
	s_waitcnt vmcnt(0)
	v_ashrrev_i32_e32 v5, 31, v4
	v_lshlrev_b64 v[4:5], 18, v[4:5]
	v_or_b32_e32 v4, s13, v4
	v_lshl_add_u64 v[8:9], s[56:57], 0, v[4:5]
	v_lshl_add_u64 v[4:5], s[58:59], 0, v[4:5]
	v_lshl_add_u64 v[8:9], v[8:9], 0, v[2:3]
	v_lshl_add_u64 v[4:5], v[4:5], 0, v[6:7]
	v_lshl_add_u64 v[10:11], v[4:5], 0, s[38:39]
	global_load_dwordx4 v[52:55], v[8:9], off offset:16
	global_load_dwordx4 v[56:59], v[8:9], off
	global_load_dwordx4 v[60:63], v[8:9], off offset:144
	global_load_dwordx4 v[64:67], v[8:9], off offset:128
	global_load_dwordx4 v[68:71], v[8:9], off offset:272
	global_load_dwordx4 v[72:75], v[8:9], off offset:256
	global_load_dwordx4 v[76:79], v[8:9], off offset:400
	global_load_dwordx4 v[80:83], v[8:9], off offset:384
	global_load_dwordx4 v[84:87], v[4:5], off
	global_load_dwordx4 v[88:91], v[4:5], off offset:256
	global_load_dwordx4 v[92:95], v[4:5], off offset:2048
	global_load_dwordx4 v[96:99], v[4:5], off offset:2304
	global_load_dwordx4 v[100:103], v[10:11], off
	global_load_dwordx4 v[104:107], v[10:11], off offset:256
	global_load_dwordx4 v[108:111], v[10:11], off offset:2048
	global_load_dwordx4 v[112:115], v[10:11], off offset:2304
	v_mov_b32_e32 v4, v3
	v_mov_b32_e32 v5, v3
	v_mov_b32_e32 v2, v3
	v_mov_b64_e32 v[22:23], v[4:5]
	v_mov_b64_e32 v[30:31], v[4:5]
	v_mov_b64_e32 v[34:35], v[4:5]
	v_mov_b64_e32 v[26:27], v[4:5]
	v_mov_b64_e32 v[10:11], v[4:5]
	v_mov_b64_e32 v[14:15], v[4:5]
	v_mov_b64_e32 v[18:19], v[4:5]
	v_mov_b64_e32 v[20:21], v[2:3]
	v_mov_b64_e32 v[28:29], v[2:3]
	v_mov_b64_e32 v[32:33], v[2:3]
	v_mov_b64_e32 v[24:25], v[2:3]
	v_mov_b64_e32 v[8:9], v[2:3]
	v_mov_b64_e32 v[12:13], v[2:3]
	v_mov_b64_e32 v[16:17], v[2:3]
	v_mov_b64_e32 v[6:7], v[4:5]
	v_mov_b64_e32 v[4:5], v[2:3]
	s_branch .LBB0_1243
.LBB0_1242:
	v_sub_f32_e32 v2, v116, v140
	v_exp_f32_e32 v2, v2
	v_sub_f32_e32 v116, v117, v140
	v_exp_f32_e32 v116, v116
	v_sub_f32_e32 v117, v118, v140
	v_exp_f32_e32 v117, v117
	v_sub_f32_e32 v118, v119, v140
	v_exp_f32_e32 v118, v118
	v_add_f32_e32 v119, 0, v2
	v_add_f32_e32 v119, v116, v119
	v_add_f32_e32 v119, v117, v119
	v_add_f32_e32 v143, v118, v119
	v_cvt_pk_bf16_f32 v116, v2, v116
	v_cvt_pk_bf16_f32 v117, v117, v118
	v_cvt_pk_bf16_f32 v118, v3, v3
	v_cvt_pk_bf16_f32 v119, v3, v3
	v_lshl_add_u64 v[132:133], v[132:133], 2, v[130:131]
	v_lshl_add_u64 v[148:149], v[132:133], 0, s[38:39]
	s_waitcnt vmcnt(13)
	v_cvt_pk_bf16_f32 v144, v84, v92
	s_waitcnt vmcnt(9)
	v_cvt_pk_bf16_f32 v145, v100, v108
	v_cvt_pk_bf16_f32 v146, v3, v3
	v_cvt_pk_bf16_f32 v147, v3, v3
	s_nop 0
	v_mfma_f32_16x16x32_bf16 v[20:23], v[144:147], v[116:119], v[20:23]
	v_cvt_pk_bf16_f32 v144, v85, v93
	v_cvt_pk_bf16_f32 v145, v101, v109
	v_cvt_pk_bf16_f32 v146, v3, v3
	v_cvt_pk_bf16_f32 v147, v3, v3
	s_nop 0
	v_mfma_f32_16x16x32_bf16 v[28:31], v[144:147], v[116:119], v[28:31]
	v_cvt_pk_bf16_f32 v144, v86, v94
	v_cvt_pk_bf16_f32 v145, v102, v110
	v_cvt_pk_bf16_f32 v146, v3, v3
	v_cvt_pk_bf16_f32 v147, v3, v3
	s_nop 0
	v_mfma_f32_16x16x32_bf16 v[32:35], v[144:147], v[116:119], v[32:35]
	v_cvt_pk_bf16_f32 v144, v87, v95
	v_cvt_pk_bf16_f32 v145, v103, v111
	v_cvt_pk_bf16_f32 v146, v3, v3
	v_cvt_pk_bf16_f32 v147, v3, v3
	global_load_dwordx4 v[84:87], v[132:133], off
	global_load_dwordx4 v[92:95], v[132:133], off offset:2048
	global_load_dwordx4 v[100:103], v[148:149], off
	global_load_dwordx4 v[108:111], v[148:149], off offset:2048
	v_mfma_f32_16x16x32_bf16 v[24:27], v[144:147], v[116:119], v[24:27]
	v_cvt_pk_bf16_f32 v144, v88, v96
	s_waitcnt vmcnt(12)
	v_cvt_pk_bf16_f32 v145, v104, v112
	v_cvt_pk_bf16_f32 v146, v3, v3
	v_cvt_pk_bf16_f32 v147, v3, v3
	s_nop 0
	v_mfma_f32_16x16x32_bf16 v[8:11], v[144:147], v[116:119], v[8:11]
	v_cvt_pk_bf16_f32 v144, v89, v97
	v_cvt_pk_bf16_f32 v145, v105, v113
	v_cvt_pk_bf16_f32 v146, v3, v3
	v_cvt_pk_bf16_f32 v147, v3, v3
	s_nop 0
	v_mfma_f32_16x16x32_bf16 v[12:15], v[144:147], v[116:119], v[12:15]
	v_cvt_pk_bf16_f32 v144, v90, v98
	v_cvt_pk_bf16_f32 v145, v106, v114
	v_cvt_pk_bf16_f32 v146, v3, v3
	v_cvt_pk_bf16_f32 v147, v3, v3
	s_nop 0
	v_mfma_f32_16x16x32_bf16 v[16:19], v[144:147], v[116:119], v[16:19]
	v_cvt_pk_bf16_f32 v144, v91, v99
	v_cvt_pk_bf16_f32 v145, v107, v115
	v_cvt_pk_bf16_f32 v146, v3, v3
	v_cvt_pk_bf16_f32 v147, v3, v3
	global_load_dwordx4 v[88:91], v[132:133], off offset:256
	global_load_dwordx4 v[96:99], v[132:133], off offset:2304
	global_load_dwordx4 v[104:107], v[148:149], off offset:256
	global_load_dwordx4 v[112:115], v[148:149], off offset:2304
	v_mfma_f32_16x16x32_bf16 v[4:7], v[144:147], v[116:119], v[4:7]
	s_add_i32 s68, s68, -16
	s_add_i32 s69, s69, 16
	s_cmpk_eq_i32 s68, 0xff00
	v_add_f32_e32 v138, v138, v143
	s_cbranch_scc1 .LBB0_1251
